# SSD output phase prompt units: chunk-state fragments of k-step 1 requested with k-step 0, k-steps 2 and 3 touched early by dummy loads
# baseline (speedup 1.0000x reference)
; __device__ __forceinline__ unsigned pk2(float lo, float hi) { const cvt_f2 v = {lo, hi}; const cvt_b2 r = __builtin_convertvector(v, cvt_b2); return __builtin_bit_cast(unsigned, r); }
; __device__ __forceinline__ void ssd_out_phase(Frame& F, bf16* Ydst) {
;     ...
;         for (int ks = 0; ks < 4; ++ks) {
;             bf16x8 af[4], bfr[4];
; #pragma unroll
;             for (int pt = 0; pt < 4; ++pt) { const int pp = 32 * (pt >> 1) + 8 * (l15 >> 2) + 4 * (pt & 1) + (l15 & 3), n0 = 32 * ks + 8 * g4;
;                 if (!smp) af[pt] = *(const bf16x8*)(ST + ((size_t)c * 64 + h) * 8192 + (((pp >> 4) * 4 + ks) * 64 + g4 * 16 + (pp & 15)) * 8);
;                 else { const float* sp = F.state_ssm + (((size_t)(c - 256) * 64 + h) * 64 + pp) * 128 + n0; const f32x4 a = *(const f32x4*)sp, b = *(const f32x4*)(sp + 4);
;                     v4u w; w.x = pk2(a.x, a.y); w.y = pk2(a.z, a.w); w.z = pk2(b.x, b.y); w.w = pk2(b.z, b.w); af[pt] = __builtin_bit_cast(bf16x8, w); } }
.LBB0_1370:
	s_or_b64 exec, exec, s[34:35]
	s_ashr_i32 s1, s0, 31
	s_lshl_b64 s[16:17], s[0:1], 20
	s_add_u32 s1, s42, s16
	s_addc_u32 s34, s43, s17
	s_lshl_b64 s[16:17], s[26:27], 14
	s_add_u32 s16, s1, s16
	v_lshrrev_b32_e32 v210, 2, v205
	s_addc_u32 s17, s34, s17
	s_addk_i32 s0, 0xff00
	s_mov_b32 s1, s27
	v_lshlrev_b32_e32 v42, 3, v210
	v_and_b32_e32 v43, 3, v209
	s_lshl_b64 s[0:1], s[0:1], 12
	s_lshl_b64 s[34:35], s[26:27], 6
	s_add_u32 s54, s34, s0
	v_or_b32_e32 v154, v42, v43
	v_cndmask_b32_e64 v2, 0, 1, s[2:3]
	v_and_b32_e32 v206, 48, v209
	s_addc_u32 s53, s35, s1
	v_cmp_ne_u32_e64 s[0:1], 1, v2
	s_andn2_b64 vcc, exec, s[2:3]
	v_lshl_or_b32 v2, v210, 7, v154
	s_movk_i32 s2, 0x10b
	s_mov_b64 s[34:35], -1
	v_and_or_b32 v122, v2, s2, v206
	s_cbranch_vccnz .LBB0_1372
	v_lshlrev_b32_e32 v2, 4, v122
	global_load_dwordx4 v[34:37], v2, s[16:17]
	global_load_dwordx4 v[134:137], v2, s[16:17] offset:1024
	global_load_dwordx4 v[228:231], v2, s[16:17] offset:2048
	global_load_dwordx4 v[232:235], v2, s[16:17] offset:3072
	s_mov_b64 s[34:35], 0

; __device__ __forceinline__ unsigned pk2(float lo, float hi) { const cvt_f2 v = {lo, hi}; const cvt_b2 r = __builtin_convertvector(v, cvt_b2); return __builtin_bit_cast(unsigned, r); }
; __device__ __forceinline__ void ssd_out_phase(Frame& F, bf16* Ydst) {
;     ...
;             for (int pt = 0; pt < 4; ++pt) { const int pp = 32 * (pt >> 1) + 8 * (l15 >> 2) + 4 * (pt & 1) + (l15 & 3), n0 = 32 * ks + 8 * g4;
;                 if (!smp) af[pt] = *(const bf16x8*)(ST + ((size_t)c * 64 + h) * 8192 + (((pp >> 4) * 4 + ks) * 64 + g4 * 16 + (pp & 15)) * 8);
;                 else { const float* sp = F.state_ssm + (((size_t)(c - 256) * 64 + h) * 64 + pp) * 128 + n0; const f32x4 a = *(const f32x4*)sp, b = *(const f32x4*)(sp + 4);
;                     v4u w; w.x = pk2(a.x, a.y); w.y = pk2(a.z, a.w); w.z = pk2(b.x, b.y); w.w = pk2(b.z, b.w); af[pt] = __builtin_bit_cast(bf16x8, w); } }
.LBB0_1374:
	v_or_b32_e32 v44, 4, v43
	v_or_b32_e32 v158, v42, v44
	v_lshl_or_b32 v4, v210, 7, v158
	s_movk_i32 s34, 0x10f
	s_mov_b64 s[2:3], -1
	s_and_b64 vcc, exec, s[0:1]
	v_and_or_b32 v123, v4, s34, v206
	s_cbranch_vccnz .LBB0_1376
	v_lshlrev_b32_e32 v4, 4, v123
	global_load_dwordx4 v[50:53], v4, s[16:17]
	global_load_dwordx4 v[138:141], v4, s[16:17] offset:1024
	global_load_dwordx4 v[236:239], v4, s[16:17] offset:2048
	global_load_dwordx4 v[240:243], v4, s[16:17] offset:3072
	s_mov_b64 s[2:3], 0

; __device__ __forceinline__ unsigned pk2(float lo, float hi) { const cvt_f2 v = {lo, hi}; const cvt_b2 r = __builtin_convertvector(v, cvt_b2); return __builtin_bit_cast(unsigned, r); }
; __device__ __forceinline__ void ssd_out_phase(Frame& F, bf16* Ydst) {
;     ...
;             for (int pt = 0; pt < 4; ++pt) { const int pp = 32 * (pt >> 1) + 8 * (l15 >> 2) + 4 * (pt & 1) + (l15 & 3), n0 = 32 * ks + 8 * g4;
;                 if (!smp) af[pt] = *(const bf16x8*)(ST + ((size_t)c * 64 + h) * 8192 + (((pp >> 4) * 4 + ks) * 64 + g4 * 16 + (pp & 15)) * 8);
;                 else { const float* sp = F.state_ssm + (((size_t)(c - 256) * 64 + h) * 64 + pp) * 128 + n0; const f32x4 a = *(const f32x4*)sp, b = *(const f32x4*)(sp + 4);
;                     v4u w; w.x = pk2(a.x, a.y); w.y = pk2(a.z, a.w); w.z = pk2(b.x, b.y); w.w = pk2(b.z, b.w); af[pt] = __builtin_bit_cast(bf16x8, w); } }
.LBB0_1378:
	v_or_b32_e32 v42, 32, v42
	v_or_b32_e32 v43, v42, v43
	v_lshl_or_b32 v4, v42, 4, v43
	s_movk_i32 s34, 0x30b
	s_mov_b64 s[2:3], -1
	s_and_b64 vcc, exec, s[0:1]
	v_and_or_b32 v4, v4, s34, v206
	s_cbranch_vccnz .LBB0_1380
	v_lshlrev_b32_e32 v45, 4, v4
	global_load_dwordx4 v[106:109], v45, s[16:17]
	global_load_dwordx4 v[142:145], v45, s[16:17] offset:1024
	global_load_dwordx4 v[244:247], v45, s[16:17] offset:2048
	global_load_dwordx4 v[228:231], v45, s[16:17] offset:3072
	s_mov_b64 s[2:3], 0

; __device__ __forceinline__ unsigned pk2(float lo, float hi) { const cvt_f2 v = {lo, hi}; const cvt_b2 r = __builtin_convertvector(v, cvt_b2); return __builtin_bit_cast(unsigned, r); }
; __device__ __forceinline__ void ssd_out_phase(Frame& F, bf16* Ydst) {
;     ...
;             for (int pt = 0; pt < 4; ++pt) { const int pp = 32 * (pt >> 1) + 8 * (l15 >> 2) + 4 * (pt & 1) + (l15 & 3), n0 = 32 * ks + 8 * g4;
;                 if (!smp) af[pt] = *(const bf16x8*)(ST + ((size_t)c * 64 + h) * 8192 + (((pp >> 4) * 4 + ks) * 64 + g4 * 16 + (pp & 15)) * 8);
;                 else { const float* sp = F.state_ssm + (((size_t)(c - 256) * 64 + h) * 64 + pp) * 128 + n0; const f32x4 a = *(const f32x4*)sp, b = *(const f32x4*)(sp + 4);
;                     v4u w; w.x = pk2(a.x, a.y); w.y = pk2(a.z, a.w); w.z = pk2(b.x, b.y); w.w = pk2(b.z, b.w); af[pt] = __builtin_bit_cast(bf16x8, w); } }
.LBB0_1382:
	v_or_b32_e32 v43, v42, v44
	v_lshl_or_b32 v42, v42, 4, v43
	s_movk_i32 s34, 0x30f
	s_mov_b64 s[2:3], -1
	s_and_b64 vcc, exec, s[0:1]
	v_and_or_b32 v185, v42, s34, v206
	s_cbranch_vccnz .LBB0_1384
	v_lshlrev_b32_e32 v42, 4, v185
	global_load_dwordx4 v[118:121], v42, s[16:17]
	global_load_dwordx4 v[146:149], v42, s[16:17] offset:1024
	global_load_dwordx4 v[232:235], v42, s[16:17] offset:2048
	global_load_dwordx4 v[236:239], v42, s[16:17] offset:3072
	s_mov_b64 s[2:3], 0

; __device__ __forceinline__ void ssd_out_phase(Frame& F, bf16* Ydst) {
;     ...
;             for (int pt = 0; pt < 4; ++pt) { const int pp = 32 * (pt >> 1) + 8 * (l15 >> 2) + 4 * (pt & 1) + (l15 & 3), n0 = 32 * ks + 8 * g4;
;                 if (!smp) af[pt] = *(const bf16x8*)(ST + ((size_t)c * 64 + h) * 8192 + (((pp >> 4) * 4 + ks) * 64 + g4 * 16 + (pp & 15)) * 8);
.LBB0_1426:
	v_lshlrev_b32_e32 v118, 4, v122
	s_nop 0
	s_cbranch_execnz .LBB0_1388

; __device__ __forceinline__ void ssd_out_phase(Frame& F, bf16* Ydst) {
;     ...
;             for (int pt = 0; pt < 4; ++pt) { const int pp = 32 * (pt >> 1) + 8 * (l15 >> 2) + 4 * (pt & 1) + (l15 & 3), n0 = 32 * ks + 8 * g4;
;                 if (!smp) af[pt] = *(const bf16x8*)(ST + ((size_t)c * 64 + h) * 8192 + (((pp >> 4) * 4 + ks) * 64 + g4 * 16 + (pp & 15)) * 8);
.LBB0_1428:
	v_lshlrev_b32_e32 v118, 4, v123
	s_nop 0
	s_cbranch_execnz .LBB0_1390

; __device__ __forceinline__ void ssd_out_phase(Frame& F, bf16* Ydst) {
;     ...
;             for (int pt = 0; pt < 4; ++pt) { const int pp = 32 * (pt >> 1) + 8 * (l15 >> 2) + 4 * (pt & 1) + (l15 & 3), n0 = 32 * ks + 8 * g4;
;                 if (!smp) af[pt] = *(const bf16x8*)(ST + ((size_t)c * 64 + h) * 8192 + (((pp >> 4) * 4 + ks) * 64 + g4 * 16 + (pp & 15)) * 8);
.LBB0_1430:
	v_lshlrev_b32_e32 v118, 4, v4
	s_nop 0
	s_cbranch_execnz .LBB0_1392

; __device__ __forceinline__ void ssd_out_phase(Frame& F, bf16* Ydst) {
;     ...
;             for (int pt = 0; pt < 4; ++pt) { const int pp = 32 * (pt >> 1) + 8 * (l15 >> 2) + 4 * (pt & 1) + (l15 & 3), n0 = 32 * ks + 8 * g4;
;                 if (!smp) af[pt] = *(const bf16x8*)(ST + ((size_t)c * 64 + h) * 8192 + (((pp >> 4) * 4 + ks) * 64 + g4 * 16 + (pp & 15)) * 8);
.LBB0_1432:
	v_lshlrev_b32_e32 v118, 4, v185
	s_nop 0
	s_cbranch_execz .LBB0_1394
	s_branch .LBB0_1395
